# phase-0 loads without the nontemporal hint
# baseline (speedup 1.0000x reference)
.Lp0_xgo:
	s_add_u32 s2, s0, s1
	s_min_u32 s2, s2, 4160
	s_cmp_lt_u32 s0, s2
	s_cbranch_scc0 .Lp0_stzero
	s_sub_u32 s50, s2, s0
	s_lshr_b32 s50, s50, 1
	v_readlane_b32 s56, v251, 24
	v_readlane_b32 s57, v251, 25
	v_readlane_b32 s58, v251, 26
	v_readlane_b32 s59, v251, 27
	s_mov_b32 s3, s0
	s_lshl_b32 s1, s0, 13
	s_add_u32 s1, s1, 0x1700000
	s_add_u32 s48, s86, s1
	s_addc_u32 s49, s87, 0
	v_lshlrev_b32_e32 v4, 5, v162
	v_lshlrev_b32_e32 v5, 4, v162
	v_add_u32_e32 v12, 0x2000, v5
	s_cmpk_lt_u32 s3, 0x1000
	s_cselect_b32 s6, s56, s58
	s_cselect_b32 s7, s57, s59
	s_cselect_b32 s2, 0, 0x1000
	s_sub_u32 s2, s3, s2
	s_lshr_b32 s1, s2, 18
	s_lshl_b32 s2, s2, 14
	s_add_u32 s16, s6, s2
	s_addc_u32 s17, s7, s1
	global_load_dwordx4 v[16:19], v4, s[16:17]
	global_load_dwordx4 v[20:23], v4, s[16:17] offset:16
	s_add_u32 s16, s16, 0x4000
	s_addc_u32 s17, s17, 0
	global_load_dwordx4 v[24:27], v4, s[16:17]
	global_load_dwordx4 v[28:31], v4, s[16:17] offset:16
	s_add_u32 s3, s3, 2
	s_cmpk_lt_u32 s3, 0x1000
	s_cselect_b32 s6, s56, s58
	s_cselect_b32 s7, s57, s59
	s_cselect_b32 s2, 0, 0x1000
	s_sub_u32 s2, s3, s2
	s_lshr_b32 s1, s2, 18
	s_lshl_b32 s2, s2, 14
	s_add_u32 s18, s6, s2
	s_addc_u32 s19, s7, s1
	global_load_dwordx4 v[32:35], v4, s[18:19]
	global_load_dwordx4 v[36:39], v4, s[18:19] offset:16
	s_add_u32 s18, s18, 0x4000
	s_addc_u32 s19, s19, 0
	global_load_dwordx4 v[40:43], v4, s[18:19]
	global_load_dwordx4 v[44:47], v4, s[18:19] offset:16
	s_add_u32 s3, s3, 2
	s_sub_u32 s50, s50, 2
.Lp0_xloop:
	s_cmp_eq_u32 s50, 0
	s_cbranch_scc1 .Lp0_xtail0
	s_cmpk_lt_u32 s3, 0x1000
	s_cselect_b32 s6, s56, s58
	s_cselect_b32 s7, s57, s59
	s_cselect_b32 s2, 0, 0x1000
	s_sub_u32 s2, s3, s2
	s_lshr_b32 s1, s2, 18
	s_lshl_b32 s2, s2, 14
	s_add_u32 s20, s6, s2
	s_addc_u32 s21, s7, s1
	global_load_dwordx4 v[48:51], v4, s[20:21]
	global_load_dwordx4 v[52:55], v4, s[20:21] offset:16
	s_add_u32 s20, s20, 0x4000
	s_addc_u32 s21, s21, 0
	global_load_dwordx4 v[56:59], v4, s[20:21]
	global_load_dwordx4 v[60:63], v4, s[20:21] offset:16
	s_add_u32 s3, s3, 2
	s_sub_u32 s50, s50, 1
	s_waitcnt vmcnt(8)
	v_cvt_pk_bf16_f32 v80, v16, v17
	v_cvt_pk_bf16_f32 v81, v18, v19
	v_cvt_pk_bf16_f32 v82, v20, v21
	v_cvt_pk_bf16_f32 v83, v22, v23
	v_cvt_pk_bf16_f32 v84, v24, v25
	v_cvt_pk_bf16_f32 v85, v26, v27
	v_cvt_pk_bf16_f32 v86, v28, v29
	v_cvt_pk_bf16_f32 v87, v30, v31
	global_store_dwordx4 v5, v[80:83], s[48:49]
	global_store_dwordx4 v12, v[84:87], s[48:49]
	s_add_u32 s48, s48, 0x4000
	s_addc_u32 s49, s49, 0
	s_cmp_eq_u32 s50, 0
	s_cbranch_scc1 .Lp0_xtail1
	s_cmpk_lt_u32 s3, 0x1000
	s_cselect_b32 s6, s56, s58
	s_cselect_b32 s7, s57, s59
	s_cselect_b32 s2, 0, 0x1000
	s_sub_u32 s2, s3, s2
	s_lshr_b32 s1, s2, 18
	s_lshl_b32 s2, s2, 14
	s_add_u32 s16, s6, s2
	s_addc_u32 s17, s7, s1
	global_load_dwordx4 v[16:19], v4, s[16:17]
	global_load_dwordx4 v[20:23], v4, s[16:17] offset:16
	s_add_u32 s16, s16, 0x4000
	s_addc_u32 s17, s17, 0
	global_load_dwordx4 v[24:27], v4, s[16:17]
	global_load_dwordx4 v[28:31], v4, s[16:17] offset:16
	s_add_u32 s3, s3, 2
	s_sub_u32 s50, s50, 1
	s_waitcnt vmcnt(8)
	v_cvt_pk_bf16_f32 v80, v32, v33
	v_cvt_pk_bf16_f32 v81, v34, v35
	v_cvt_pk_bf16_f32 v82, v36, v37
	v_cvt_pk_bf16_f32 v83, v38, v39
	v_cvt_pk_bf16_f32 v84, v40, v41
	v_cvt_pk_bf16_f32 v85, v42, v43
	v_cvt_pk_bf16_f32 v86, v44, v45
	v_cvt_pk_bf16_f32 v87, v46, v47
	global_store_dwordx4 v5, v[80:83], s[48:49]
	global_store_dwordx4 v12, v[84:87], s[48:49]
	s_add_u32 s48, s48, 0x4000
	s_addc_u32 s49, s49, 0
	s_cmp_eq_u32 s50, 0
	s_cbranch_scc1 .Lp0_xtail2
	s_cmpk_lt_u32 s3, 0x1000
	s_cselect_b32 s6, s56, s58
	s_cselect_b32 s7, s57, s59
	s_cselect_b32 s2, 0, 0x1000
	s_sub_u32 s2, s3, s2
	s_lshr_b32 s1, s2, 18
	s_lshl_b32 s2, s2, 14
	s_add_u32 s18, s6, s2
	s_addc_u32 s19, s7, s1
	global_load_dwordx4 v[32:35], v4, s[18:19]
	global_load_dwordx4 v[36:39], v4, s[18:19] offset:16
	s_add_u32 s18, s18, 0x4000
	s_addc_u32 s19, s19, 0
	global_load_dwordx4 v[40:43], v4, s[18:19]
	global_load_dwordx4 v[44:47], v4, s[18:19] offset:16
	s_add_u32 s3, s3, 2
	s_sub_u32 s50, s50, 1
	s_waitcnt vmcnt(8)
	v_cvt_pk_bf16_f32 v80, v48, v49
	v_cvt_pk_bf16_f32 v81, v50, v51
	v_cvt_pk_bf16_f32 v82, v52, v53
	v_cvt_pk_bf16_f32 v83, v54, v55
	v_cvt_pk_bf16_f32 v84, v56, v57
	v_cvt_pk_bf16_f32 v85, v58, v59
	v_cvt_pk_bf16_f32 v86, v60, v61
	v_cvt_pk_bf16_f32 v87, v62, v63
	global_store_dwordx4 v5, v[80:83], s[48:49]
	global_store_dwordx4 v12, v[84:87], s[48:49]
	s_add_u32 s48, s48, 0x4000
	s_addc_u32 s49, s49, 0
	s_branch .Lp0_xloop
